# grid barrier: all workgroups spin on monotonic TOP counter (no TOPGEN/XGEN release hops)
# speedup vs baseline: 1.0042x; 1.0042x over previous
; __device__ __forceinline__ unsigned xb_ld(unsigned* p)              { return __hip_atomic_load(p, __ATOMIC_RELAXED, __HIP_MEMORY_SCOPE_AGENT); }
; __device__ __forceinline__ unsigned xb_add(unsigned* p, unsigned v) { return __hip_atomic_fetch_add(p, v, __ATOMIC_RELAXED, __HIP_MEMORY_SCOPE_AGENT); }
; #define XB_SPIN(cond, bar) do { unsigned _sp = 0; while (cond) { __builtin_amdgcn_s_sleep(1); \
;     if ((++_sp & 255u) == 0u) { if (xb_ld(&(bar)[XB_TMO])) break; if (_sp > XB_SPIN_CAP) { atomicAdd(&(bar)[XB_TMO], 1u); break; } } } } while (0)
; __device__ __forceinline__ void xcd_barrier(const XcdBarrier& b) {
;     ...
;         const unsigned old = xb_add(&bar[XB_XSUB(b.x)], 1u);
;         const unsigned gen = old / nloc;
;         if (old + 1u == (gen + 1u) * nloc) {
;             __builtin_amdgcn_fence(__ATOMIC_RELEASE, "agent");
;             asm volatile("s_waitcnt vmcnt(0)" ::: "memory");
;             const unsigned og = xb_add(&bar[XB_TOP], 1u);
;             const unsigned tg = og / nx;
;             if (og + 1u == (tg + 1u) * nx) xb_add(&bar[XB_TOPGEN], 1u);
;             else XB_SPIN(xb_ld(&bar[XB_TOPGEN]) == tg, bar);
;             __builtin_amdgcn_fence(__ATOMIC_ACQUIRE, "agent");
;             xb_add(&bar[XB_XGEN(b.x)], 1u);
;             asm volatile("s_waitcnt vmcnt(0)" ::: "memory");
;         } else {
;             XB_SPIN(xb_ld(&bar[XB_XGEN(b.x)]) == gen, bar);
.LBB0_600:
	s_or_b64 exec, exec, s[10:11]
	v_cvt_f32_u32_e32 v4, v2
	s_waitcnt vmcnt(0)
	v_readfirstlane_b32 s8, v3
	v_sub_u32_e32 v3, 0, v2
	v_rcp_iflag_f32_e32 v4, v4
	v_add_u32_e32 v5, s8, v1
	v_mul_f32_e32 v4, 0x4f7ffffe, v4
	v_cvt_u32_f32_e32 v4, v4
	v_mul_lo_u32 v1, v3, v4
	v_mul_hi_u32 v1, v4, v1
	v_add_u32_e32 v1, v4, v1
	v_mul_hi_u32 v1, v5, v1
	v_mul_lo_u32 v3, v1, v2
	v_sub_u32_e32 v3, v5, v3
	v_add_u32_e32 v4, 1, v1
	v_cmp_ge_u32_e32 vcc, v3, v2
	s_nop 1
	v_cndmask_b32_e32 v1, v1, v4, vcc
	v_sub_u32_e32 v4, v3, v2
	v_cndmask_b32_e32 v3, v3, v4, vcc
	v_add_u32_e32 v4, 1, v1
	v_cmp_ge_u32_e32 vcc, v3, v2
	v_add_u32_e32 v3, 1, v5
	s_nop 0
	v_cndmask_b32_e32 v1, v1, v4, vcc
	v_mul_lo_u32 v4, v2, v1
	v_add_u32_e32 v2, v4, v2
	v_cmp_ne_u32_e32 vcc, v3, v2
	s_and_saveexec_b64 s[8:9], vcc
	s_xor_b64 s[8:9], exec, s[8:9]
	s_cbranch_execz .LBB0_614
	s_waitcnt lgkmcnt(0)
	v_add_u32_e32 v4, 1, v1
	v_mul_lo_u32 v4, v4, v0
	v_mov_b32_e32 v0, 0x3000
	global_load_dword v0, v0, s[4:5] offset:1024 sc1
	s_add_u32 s12, s4, 0x3400
	s_addc_u32 s13, s5, 0
	s_waitcnt vmcnt(0)
	v_cmp_lt_u32_e32 vcc, v0, v4
	s_and_saveexec_b64 s[10:11], vcc
	s_cbranch_execz .LBB0_613
	s_mov_b32 s24, 1
	s_mov_b64 s[14:15], 0
	s_branch .LBB0_604

; __device__ __forceinline__ unsigned xb_ld(unsigned* p)              { return __hip_atomic_load(p, __ATOMIC_RELAXED, __HIP_MEMORY_SCOPE_AGENT); }
; #define XB_SPIN(cond, bar) do { unsigned _sp = 0; while (cond) { __builtin_amdgcn_s_sleep(1); \
;     if ((++_sp & 255u) == 0u) { if (xb_ld(&(bar)[XB_TMO])) break; if (_sp > XB_SPIN_CAP) { atomicAdd(&(bar)[XB_TMO], 1u); break; } } } } while (0)
; __device__ __forceinline__ void xcd_barrier(const XcdBarrier& b) {
;     ...
;             XB_SPIN(xb_ld(&bar[XB_XGEN(b.x)]) == gen, bar);
.LBB0_606:
	global_load_dword v0, v33, s[12:13] sc1
	s_add_i32 s24, s24, 1
	s_mov_b64 s[20:21], -1
	s_waitcnt vmcnt(0)
	v_cmp_ge_u32_e32 vcc, v0, v4
	s_orn2_b64 s[18:19], vcc, exec
	s_branch .LBB0_603

; __device__ __forceinline__ unsigned xb_ld(unsigned* p)              { return __hip_atomic_load(p, __ATOMIC_RELAXED, __HIP_MEMORY_SCOPE_AGENT); }
; __device__ __forceinline__ unsigned xb_add(unsigned* p, unsigned v) { return __hip_atomic_fetch_add(p, v, __ATOMIC_RELAXED, __HIP_MEMORY_SCOPE_AGENT); }
; #define XB_SPIN(cond, bar) do { unsigned _sp = 0; while (cond) { __builtin_amdgcn_s_sleep(1); \
;     if ((++_sp & 255u) == 0u) { if (xb_ld(&(bar)[XB_TMO])) break; if (_sp > XB_SPIN_CAP) { atomicAdd(&(bar)[XB_TMO], 1u); break; } } } } while (0)
; __device__ __forceinline__ void xcd_barrier(const XcdBarrier& b) {
;     ...
;             const unsigned og = xb_add(&bar[XB_TOP], 1u);
;             const unsigned tg = og / nx;
;             if (og + 1u == (tg + 1u) * nx) xb_add(&bar[XB_TOPGEN], 1u);
;             else XB_SPIN(xb_ld(&bar[XB_TOPGEN]) == tg, bar);
.LBB0_617:
	s_or_b64 exec, exec, s[10:11]
	v_cvt_f32_u32_e32 v3, v0
	s_waitcnt vmcnt(0)
	v_readfirstlane_b32 s8, v2
	s_mov_b64 s[12:13], 0
	v_rcp_iflag_f32_e32 v3, v3
	v_add_u32_e32 v1, s8, v1
	v_add_u32_e32 v4, 1, v1
	s_add_u32 s8, s4, 0x3400
	v_mul_f32_e32 v2, 0x4f7ffffe, v3
	v_cvt_u32_f32_e32 v2, v2
	v_sub_u32_e32 v3, 0, v0
	s_addc_u32 s9, s5, 0
	v_mul_lo_u32 v3, v3, v2
	v_mul_hi_u32 v3, v2, v3
	v_add_u32_e32 v2, v2, v3
	v_mul_hi_u32 v2, v1, v2
	v_mul_lo_u32 v3, v2, v0
	v_sub_u32_e32 v1, v1, v3
	v_add_u32_e32 v5, 1, v2
	v_cmp_ge_u32_e32 vcc, v1, v0
	v_sub_u32_e32 v3, v1, v0
	s_nop 0
	v_cndmask_b32_e32 v2, v2, v5, vcc
	v_cndmask_b32_e32 v1, v1, v3, vcc
	v_add_u32_e32 v3, 1, v2
	v_cmp_ge_u32_e32 vcc, v1, v0
	s_nop 1
	v_cndmask_b32_e32 v2, v2, v3, vcc
	v_mul_lo_u32 v1, v0, v2
	v_add_u32_e32 v0, v1, v0
	v_mov_b32_e32 v5, v0
	v_cmp_ne_u32_e32 vcc, v4, v0
	v_mov_b64_e32 v[0:1], s[8:9]
	s_and_saveexec_b64 s[10:11], vcc
	s_cbranch_execz .LBB0_629
	global_load_dword v0, v33, s[8:9] sc1
	s_mov_b64 s[16:17], 0
	s_waitcnt vmcnt(0)
	v_cmp_lt_u32_e32 vcc, v0, v5
	s_and_saveexec_b64 s[14:15], vcc
	s_cbranch_execz .LBB0_628
	s_add_u32 s12, s4, 0x200
	s_addc_u32 s13, s5, 0
	s_mov_b32 s24, 1
	s_mov_b64 s[4:5], 0
	s_branch .LBB0_621

; __device__ __forceinline__ unsigned xb_ld(unsigned* p)              { return __hip_atomic_load(p, __ATOMIC_RELAXED, __HIP_MEMORY_SCOPE_AGENT); }
; #define XB_SPIN(cond, bar) do { unsigned _sp = 0; while (cond) { __builtin_amdgcn_s_sleep(1); \
;     if ((++_sp & 255u) == 0u) { if (xb_ld(&(bar)[XB_TMO])) break; if (_sp > XB_SPIN_CAP) { atomicAdd(&(bar)[XB_TMO], 1u); break; } } } } while (0)
; __device__ __forceinline__ void xcd_barrier(const XcdBarrier& b) {
;     ...
;             else XB_SPIN(xb_ld(&bar[XB_TOPGEN]) == tg, bar);
.LBB0_623:
	global_load_dword v0, v33, s[8:9] sc1
	s_add_i32 s24, s24, 1
	s_mov_b64 s[20:21], -1
	s_waitcnt vmcnt(0)
	v_cmp_ge_u32_e32 vcc, v0, v5
	s_orn2_b64 s[18:19], vcc, exec
	s_branch .LBB0_620

; __device__ __forceinline__ unsigned xb_add(unsigned* p, unsigned v) { return __hip_atomic_fetch_add(p, v, __ATOMIC_RELAXED, __HIP_MEMORY_SCOPE_AGENT); }
; __device__ __forceinline__ void xcd_barrier(const XcdBarrier& b) {
;     ...
;             __builtin_amdgcn_fence(__ATOMIC_ACQUIRE, "agent");
;             xb_add(&bar[XB_XGEN(b.x)], 1u);
;             asm volatile("s_waitcnt vmcnt(0)" ::: "memory");
.LBB0_631:
	s_or_b64 exec, exec, s[4:5]
	s_mov_b64 s[4:5], exec
	v_mbcnt_lo_u32_b32 v0, s4, 0
	v_mbcnt_hi_u32_b32 v0, s5, v0
	v_cmp_eq_u32_e32 vcc, 0, v0
	s_waitcnt vmcnt(0)
	buffer_inv sc1
	s_and_saveexec_b64 s[8:9], vcc
	s_cbranch_execz .LBB0_633
	s_bcnt1_i32_b64 s4, s[4:5]
	v_mov_b32_e32 v0, s4
	v_mov_b32_e32 v1, 0x2000
.LBB0_633:
	s_or_b64 exec, exec, s[8:9]
	s_waitcnt vmcnt(0)

; __device__ __forceinline__ unsigned xb_add(unsigned* p, unsigned v) { return __hip_atomic_fetch_add(p, v, __ATOMIC_RELAXED, __HIP_MEMORY_SCOPE_AGENT); }
; __device__ __forceinline__ void xcd_barrier(const XcdBarrier& b) {
;     ...
;             __builtin_amdgcn_fence(__ATOMIC_ACQUIRE, "agent");
;             xb_add(&bar[XB_XGEN(b.x)], 1u);
;             asm volatile("s_waitcnt vmcnt(0)" ::: "memory");
.LBB0_779:
	s_or_b64 exec, exec, s[4:5]
	s_mov_b64 s[4:5], exec
	v_mbcnt_lo_u32_b32 v0, s4, 0
	v_mbcnt_hi_u32_b32 v0, s5, v0
	v_cmp_eq_u32_e32 vcc, 0, v0
	s_waitcnt vmcnt(0)
	buffer_inv sc1
	s_and_saveexec_b64 s[8:9], vcc
	s_cbranch_execz .LBB0_781
	s_bcnt1_i32_b64 s4, s[4:5]
	v_mov_b32_e32 v0, s4
	v_mov_b32_e32 v1, 0x2000
.LBB0_781:
	s_or_b64 exec, exec, s[8:9]
	s_waitcnt vmcnt(0)

; __device__ __forceinline__ unsigned xb_add(unsigned* p, unsigned v) { return __hip_atomic_fetch_add(p, v, __ATOMIC_RELAXED, __HIP_MEMORY_SCOPE_AGENT); }
; __device__ __forceinline__ void xcd_barrier(const XcdBarrier& b) {
;     ...
;             __builtin_amdgcn_fence(__ATOMIC_ACQUIRE, "agent");
;             xb_add(&bar[XB_XGEN(b.x)], 1u);
;             asm volatile("s_waitcnt vmcnt(0)" ::: "memory");
.LBB0_979:
	s_or_b64 exec, exec, s[4:5]
	s_mov_b64 s[4:5], exec
	v_mbcnt_lo_u32_b32 v0, s4, 0
	v_mbcnt_hi_u32_b32 v0, s5, v0
	v_cmp_eq_u32_e32 vcc, 0, v0
	s_waitcnt vmcnt(0)
	buffer_inv sc1
	s_and_saveexec_b64 s[8:9], vcc
	s_cbranch_execz .LBB0_981
	s_bcnt1_i32_b64 s4, s[4:5]
	v_mov_b32_e32 v0, s4
	v_mov_b32_e32 v1, 0x2000
.LBB0_981:
	s_or_b64 exec, exec, s[8:9]
	s_waitcnt vmcnt(0)

; __device__ __forceinline__ unsigned xb_add(unsigned* p, unsigned v) { return __hip_atomic_fetch_add(p, v, __ATOMIC_RELAXED, __HIP_MEMORY_SCOPE_AGENT); }
; __device__ __forceinline__ void xcd_barrier(const XcdBarrier& b) {
;     ...
;             __builtin_amdgcn_fence(__ATOMIC_ACQUIRE, "agent");
;             xb_add(&bar[XB_XGEN(b.x)], 1u);
;             asm volatile("s_waitcnt vmcnt(0)" ::: "memory");
.LBB0_1172:
	s_or_b64 exec, exec, s[4:5]
	s_mov_b64 s[4:5], exec
	v_mbcnt_lo_u32_b32 v0, s4, 0
	v_mbcnt_hi_u32_b32 v0, s5, v0
	v_cmp_eq_u32_e32 vcc, 0, v0
	s_waitcnt vmcnt(0)
	buffer_inv sc1
	s_and_saveexec_b64 s[8:9], vcc
	s_cbranch_execz .LBB0_1174
	s_bcnt1_i32_b64 s4, s[4:5]
	v_mov_b32_e32 v0, s4
	v_mov_b32_e32 v1, 0x2000
.LBB0_1174:
	s_or_b64 exec, exec, s[8:9]
	s_waitcnt vmcnt(0)

; __device__ __forceinline__ unsigned xb_add(unsigned* p, unsigned v) { return __hip_atomic_fetch_add(p, v, __ATOMIC_RELAXED, __HIP_MEMORY_SCOPE_AGENT); }
; __device__ __forceinline__ void xcd_barrier(const XcdBarrier& b) {
;     ...
;             __builtin_amdgcn_fence(__ATOMIC_ACQUIRE, "agent");
;             xb_add(&bar[XB_XGEN(b.x)], 1u);
;             asm volatile("s_waitcnt vmcnt(0)" ::: "memory");
.LBB0_1683:
	s_or_b64 exec, exec, s[4:5]
	s_mov_b64 s[4:5], exec
	v_mbcnt_lo_u32_b32 v0, s4, 0
	v_mbcnt_hi_u32_b32 v0, s5, v0
	v_cmp_eq_u32_e32 vcc, 0, v0
	s_waitcnt vmcnt(0)
	buffer_inv sc1
	s_and_saveexec_b64 s[8:9], vcc
	s_cbranch_execz .LBB0_1685
	s_bcnt1_i32_b64 s4, s[4:5]
	v_mov_b32_e32 v0, s4
	v_mov_b32_e32 v1, 0x2000
.LBB0_1685:
	s_or_b64 exec, exec, s[8:9]
	s_waitcnt vmcnt(0)

; __device__ __forceinline__ unsigned xb_add(unsigned* p, unsigned v) { return __hip_atomic_fetch_add(p, v, __ATOMIC_RELAXED, __HIP_MEMORY_SCOPE_AGENT); }
; __device__ __forceinline__ void xcd_barrier(const XcdBarrier& b) {
;     ...
;             __builtin_amdgcn_fence(__ATOMIC_ACQUIRE, "agent");
;             xb_add(&bar[XB_XGEN(b.x)], 1u);
;             asm volatile("s_waitcnt vmcnt(0)" ::: "memory");
.LBB0_1813:
	s_or_b64 exec, exec, s[4:5]
	s_mov_b64 s[4:5], exec
	v_mbcnt_lo_u32_b32 v0, s4, 0
	v_mbcnt_hi_u32_b32 v0, s5, v0
	v_cmp_eq_u32_e32 vcc, 0, v0
	s_waitcnt vmcnt(0)
	buffer_inv sc1
	s_and_saveexec_b64 s[8:9], vcc
	s_cbranch_execz .LBB0_1815
	s_bcnt1_i32_b64 s4, s[4:5]
	v_mov_b32_e32 v0, s4
	v_mov_b32_e32 v1, 0x2000
.LBB0_1815:
	s_or_b64 exec, exec, s[8:9]
	s_waitcnt vmcnt(0)

; __device__ __forceinline__ unsigned xb_add(unsigned* p, unsigned v) { return __hip_atomic_fetch_add(p, v, __ATOMIC_RELAXED, __HIP_MEMORY_SCOPE_AGENT); }
; __device__ __forceinline__ void xcd_barrier(const XcdBarrier& b) {
;     ...
;             __builtin_amdgcn_fence(__ATOMIC_ACQUIRE, "agent");
;             xb_add(&bar[XB_XGEN(b.x)], 1u);
;             asm volatile("s_waitcnt vmcnt(0)" ::: "memory");
.LBB0_2013:
	s_or_b64 exec, exec, s[4:5]
	s_mov_b64 s[4:5], exec
	v_mbcnt_lo_u32_b32 v0, s4, 0
	v_mbcnt_hi_u32_b32 v0, s5, v0
	v_cmp_eq_u32_e32 vcc, 0, v0
	s_waitcnt vmcnt(0)
	buffer_inv sc1
	s_and_saveexec_b64 s[8:9], vcc
	s_cbranch_execz .LBB0_2015
	s_bcnt1_i32_b64 s4, s[4:5]
	v_mov_b32_e32 v0, s4
	v_mov_b32_e32 v1, 0x2000
.LBB0_2015:
	s_or_b64 exec, exec, s[8:9]
	s_waitcnt vmcnt(0)

; __device__ __forceinline__ unsigned xb_ld(unsigned* p)              { return __hip_atomic_load(p, __ATOMIC_RELAXED, __HIP_MEMORY_SCOPE_AGENT); }
; __device__ __forceinline__ unsigned xb_add(unsigned* p, unsigned v) { return __hip_atomic_fetch_add(p, v, __ATOMIC_RELAXED, __HIP_MEMORY_SCOPE_AGENT); }
; #define XB_SPIN(cond, bar) do { unsigned _sp = 0; while (cond) { __builtin_amdgcn_s_sleep(1); \
;     if ((++_sp & 255u) == 0u) { if (xb_ld(&(bar)[XB_TMO])) break; if (_sp > XB_SPIN_CAP) { atomicAdd(&(bar)[XB_TMO], 1u); break; } } } } while (0)
; __device__ __forceinline__ void xcd_barrier(const XcdBarrier& b) {
;     ...
;         const unsigned old = xb_add(&bar[XB_XSUB(b.x)], 1u);
;         const unsigned gen = old / nloc;
;         if (old + 1u == (gen + 1u) * nloc) {
;             __builtin_amdgcn_fence(__ATOMIC_RELEASE, "agent");
;             asm volatile("s_waitcnt vmcnt(0)" ::: "memory");
;             const unsigned og = xb_add(&bar[XB_TOP], 1u);
;             const unsigned tg = og / nx;
;             if (og + 1u == (tg + 1u) * nx) xb_add(&bar[XB_TOPGEN], 1u);
;             else XB_SPIN(xb_ld(&bar[XB_TOPGEN]) == tg, bar);
;             __builtin_amdgcn_fence(__ATOMIC_ACQUIRE, "agent");
;             xb_add(&bar[XB_XGEN(b.x)], 1u);
;             asm volatile("s_waitcnt vmcnt(0)" ::: "memory");
;         } else {
;             XB_SPIN(xb_ld(&bar[XB_XGEN(b.x)]) == gen, bar);
.LBB0_2073:
	s_or_b64 exec, exec, s[14:15]
	v_cvt_f32_u32_e32 v4, v2
	s_waitcnt vmcnt(0)
	v_readfirstlane_b32 s12, v3
	v_sub_u32_e32 v3, 0, v2
	v_rcp_iflag_f32_e32 v4, v4
	v_add_u32_e32 v5, s12, v1
	v_mul_f32_e32 v4, 0x4f7ffffe, v4
	v_cvt_u32_f32_e32 v4, v4
	v_mul_lo_u32 v1, v3, v4
	v_mul_hi_u32 v1, v4, v1
	v_add_u32_e32 v1, v4, v1
	v_mul_hi_u32 v1, v5, v1
	v_mul_lo_u32 v3, v1, v2
	v_sub_u32_e32 v3, v5, v3
	v_add_u32_e32 v4, 1, v1
	v_cmp_ge_u32_e32 vcc, v3, v2
	s_nop 1
	v_cndmask_b32_e32 v1, v1, v4, vcc
	v_sub_u32_e32 v4, v3, v2
	v_cndmask_b32_e32 v3, v3, v4, vcc
	v_add_u32_e32 v4, 1, v1
	v_cmp_ge_u32_e32 vcc, v3, v2
	v_add_u32_e32 v3, 1, v5
	s_nop 0
	v_cndmask_b32_e32 v1, v1, v4, vcc
	v_mul_lo_u32 v4, v2, v1
	v_add_u32_e32 v2, v4, v2
	v_cmp_ne_u32_e32 vcc, v3, v2
	s_and_saveexec_b64 s[12:13], vcc
	s_xor_b64 s[12:13], exec, s[12:13]
	s_cbranch_execz .LBB0_2087
	s_waitcnt lgkmcnt(0)
	v_add_u32_e32 v4, 1, v1
	v_mul_lo_u32 v4, v4, v0
	v_mov_b32_e32 v0, 0x3000
	global_load_dword v0, v0, s[6:7] offset:1024 sc1
	s_add_u32 s26, s6, 0x3400
	s_addc_u32 s27, s7, 0
	s_waitcnt vmcnt(0)
	v_cmp_lt_u32_e32 vcc, v0, v4
	s_and_saveexec_b64 s[14:15], vcc
	s_cbranch_execz .LBB0_2086
	s_mov_b32 s40, 1
	s_mov_b64 s[28:29], 0
	s_branch .LBB0_2077

; __device__ __forceinline__ unsigned xb_ld(unsigned* p)              { return __hip_atomic_load(p, __ATOMIC_RELAXED, __HIP_MEMORY_SCOPE_AGENT); }
; #define XB_SPIN(cond, bar) do { unsigned _sp = 0; while (cond) { __builtin_amdgcn_s_sleep(1); \
;     if ((++_sp & 255u) == 0u) { if (xb_ld(&(bar)[XB_TMO])) break; if (_sp > XB_SPIN_CAP) { atomicAdd(&(bar)[XB_TMO], 1u); break; } } } } while (0)
; __device__ __forceinline__ void xcd_barrier(const XcdBarrier& b) {
;     ...
;             XB_SPIN(xb_ld(&bar[XB_XGEN(b.x)]) == gen, bar);
.LBB0_2079:
	global_load_dword v0, v33, s[26:27] sc1
	s_add_i32 s40, s40, 1
	s_mov_b64 s[36:37], -1
	s_waitcnt vmcnt(0)
	v_cmp_ge_u32_e32 vcc, v0, v4
	s_orn2_b64 s[34:35], vcc, exec
	s_branch .LBB0_2076

; __device__ __forceinline__ unsigned xb_ld(unsigned* p)              { return __hip_atomic_load(p, __ATOMIC_RELAXED, __HIP_MEMORY_SCOPE_AGENT); }
; __device__ __forceinline__ unsigned xb_add(unsigned* p, unsigned v) { return __hip_atomic_fetch_add(p, v, __ATOMIC_RELAXED, __HIP_MEMORY_SCOPE_AGENT); }
; #define XB_SPIN(cond, bar) do { unsigned _sp = 0; while (cond) { __builtin_amdgcn_s_sleep(1); \
;     if ((++_sp & 255u) == 0u) { if (xb_ld(&(bar)[XB_TMO])) break; if (_sp > XB_SPIN_CAP) { atomicAdd(&(bar)[XB_TMO], 1u); break; } } } } while (0)
; __device__ __forceinline__ void xcd_barrier(const XcdBarrier& b) {
;     ...
;             const unsigned og = xb_add(&bar[XB_TOP], 1u);
;             const unsigned tg = og / nx;
;             if (og + 1u == (tg + 1u) * nx) xb_add(&bar[XB_TOPGEN], 1u);
;             else XB_SPIN(xb_ld(&bar[XB_TOPGEN]) == tg, bar);
.LBB0_2090:
	s_or_b64 exec, exec, s[14:15]
	s_waitcnt vmcnt(0)
	v_readfirstlane_b32 s12, v2
	v_cvt_f32_u32_e32 v2, v0
	v_sub_u32_e32 v3, 0, v0
	v_add_u32_e32 v1, s12, v1
	s_add_u32 s12, s6, 0x3400
	v_rcp_iflag_f32_e32 v2, v2
	s_addc_u32 s13, s7, 0
	s_mov_b64 s[26:27], 0
	v_mul_f32_e32 v2, 0x4f7ffffe, v2
	v_cvt_u32_f32_e32 v2, v2
	v_mul_lo_u32 v3, v3, v2
	v_mul_hi_u32 v3, v2, v3
	v_add_u32_e32 v2, v2, v3
	v_mul_hi_u32 v2, v1, v2
	v_mul_lo_u32 v3, v2, v0
	v_sub_u32_e32 v3, v1, v3
	v_cmp_ge_u32_e32 vcc, v3, v0
	v_add_u32_e32 v4, 1, v2
	v_add_u32_e32 v1, 1, v1
	v_cndmask_b32_e32 v2, v2, v4, vcc
	v_sub_u32_e32 v4, v3, v0
	v_cndmask_b32_e32 v3, v3, v4, vcc
	v_cmp_ge_u32_e32 vcc, v3, v0
	v_add_u32_e32 v3, 1, v2
	s_nop 0
	v_cndmask_b32_e32 v2, v2, v3, vcc
	v_mul_lo_u32 v3, v0, v2
	v_add_u32_e32 v0, v3, v0
	v_mov_b32_e32 v5, v0
	v_cmp_ne_u32_e32 vcc, v1, v0
	v_mov_b64_e32 v[0:1], s[12:13]
	s_and_saveexec_b64 s[14:15], vcc
	s_cbranch_execz .LBB0_2102
	global_load_dword v0, v33, s[12:13] sc1
	s_mov_b64 s[30:31], 0
	s_waitcnt vmcnt(0)
	v_cmp_lt_u32_e32 vcc, v0, v5
	s_and_saveexec_b64 s[28:29], vcc
	s_cbranch_execz .LBB0_2101
	s_add_u32 s26, s6, 0x200
	s_addc_u32 s27, s7, 0
	s_mov_b32 s40, 1
	s_mov_b64 s[6:7], 0
	s_branch .LBB0_2094

; __device__ __forceinline__ unsigned xb_ld(unsigned* p)              { return __hip_atomic_load(p, __ATOMIC_RELAXED, __HIP_MEMORY_SCOPE_AGENT); }
; #define XB_SPIN(cond, bar) do { unsigned _sp = 0; while (cond) { __builtin_amdgcn_s_sleep(1); \
;     if ((++_sp & 255u) == 0u) { if (xb_ld(&(bar)[XB_TMO])) break; if (_sp > XB_SPIN_CAP) { atomicAdd(&(bar)[XB_TMO], 1u); break; } } } } while (0)
; __device__ __forceinline__ void xcd_barrier(const XcdBarrier& b) {
;     ...
;             else XB_SPIN(xb_ld(&bar[XB_TOPGEN]) == tg, bar);
.LBB0_2096:
	global_load_dword v0, v33, s[12:13] sc1
	s_add_i32 s40, s40, 1
	s_mov_b64 s[36:37], -1
	s_waitcnt vmcnt(0)
	v_cmp_ge_u32_e32 vcc, v0, v5
	s_orn2_b64 s[34:35], vcc, exec
	s_branch .LBB0_2093

; __device__ __forceinline__ unsigned xb_add(unsigned* p, unsigned v) { return __hip_atomic_fetch_add(p, v, __ATOMIC_RELAXED, __HIP_MEMORY_SCOPE_AGENT); }
; __device__ __forceinline__ void xcd_barrier(const XcdBarrier& b) {
;     ...
;             __builtin_amdgcn_fence(__ATOMIC_ACQUIRE, "agent");
;             xb_add(&bar[XB_XGEN(b.x)], 1u);
;             asm volatile("s_waitcnt vmcnt(0)" ::: "memory");
.LBB0_2104:
	s_or_b64 exec, exec, s[6:7]
	s_mov_b64 s[6:7], exec
	v_mbcnt_lo_u32_b32 v0, s6, 0
	v_mbcnt_hi_u32_b32 v0, s7, v0
	v_cmp_eq_u32_e32 vcc, 0, v0
	s_waitcnt vmcnt(0)
	buffer_inv sc1
	s_and_saveexec_b64 s[12:13], vcc
	s_cbranch_execz .LBB0_2106
	s_bcnt1_i32_b64 s6, s[6:7]
	v_mov_b32_e32 v0, s6
	v_mov_b32_e32 v1, 0x2000
.LBB0_2106:
	s_or_b64 exec, exec, s[12:13]
	s_waitcnt vmcnt(0)

; __device__ __forceinline__ unsigned xb_ld(unsigned* p)              { return __hip_atomic_load(p, __ATOMIC_RELAXED, __HIP_MEMORY_SCOPE_AGENT); }
; __device__ __forceinline__ unsigned xb_add(unsigned* p, unsigned v) { return __hip_atomic_fetch_add(p, v, __ATOMIC_RELAXED, __HIP_MEMORY_SCOPE_AGENT); }
; #define XB_SPIN(cond, bar) do { unsigned _sp = 0; while (cond) { __builtin_amdgcn_s_sleep(1); \
;     if ((++_sp & 255u) == 0u) { if (xb_ld(&(bar)[XB_TMO])) break; if (_sp > XB_SPIN_CAP) { atomicAdd(&(bar)[XB_TMO], 1u); break; } } } } while (0)
; __device__ __forceinline__ void xcd_barrier(const XcdBarrier& b) {
;     ...
;         const unsigned old = xb_add(&bar[XB_XSUB(b.x)], 1u);
;         const unsigned gen = old / nloc;
;         if (old + 1u == (gen + 1u) * nloc) {
;             __builtin_amdgcn_fence(__ATOMIC_RELEASE, "agent");
;             asm volatile("s_waitcnt vmcnt(0)" ::: "memory");
;             const unsigned og = xb_add(&bar[XB_TOP], 1u);
;             const unsigned tg = og / nx;
;             if (og + 1u == (tg + 1u) * nx) xb_add(&bar[XB_TOPGEN], 1u);
;             else XB_SPIN(xb_ld(&bar[XB_TOPGEN]) == tg, bar);
;             __builtin_amdgcn_fence(__ATOMIC_ACQUIRE, "agent");
;             xb_add(&bar[XB_XGEN(b.x)], 1u);
;             asm volatile("s_waitcnt vmcnt(0)" ::: "memory");
;         } else {
;             XB_SPIN(xb_ld(&bar[XB_XGEN(b.x)]) == gen, bar);
.LBB0_2287:
	s_or_b64 exec, exec, s[12:13]
	v_cvt_f32_u32_e32 v4, v2
	s_waitcnt vmcnt(0)
	v_readfirstlane_b32 s8, v3
	v_sub_u32_e32 v3, 0, v2
	v_rcp_iflag_f32_e32 v4, v4
	v_add_u32_e32 v5, s8, v1
	v_mul_f32_e32 v4, 0x4f7ffffe, v4
	v_cvt_u32_f32_e32 v4, v4
	v_mul_lo_u32 v1, v3, v4
	v_mul_hi_u32 v1, v4, v1
	v_add_u32_e32 v1, v4, v1
	v_mul_hi_u32 v1, v5, v1
	v_mul_lo_u32 v3, v1, v2
	v_sub_u32_e32 v3, v5, v3
	v_add_u32_e32 v4, 1, v1
	v_cmp_ge_u32_e32 vcc, v3, v2
	s_nop 1
	v_cndmask_b32_e32 v1, v1, v4, vcc
	v_sub_u32_e32 v4, v3, v2
	v_cndmask_b32_e32 v3, v3, v4, vcc
	v_add_u32_e32 v4, 1, v1
	v_cmp_ge_u32_e32 vcc, v3, v2
	v_add_u32_e32 v3, 1, v5
	s_nop 0
	v_cndmask_b32_e32 v1, v1, v4, vcc
	v_mul_lo_u32 v4, v2, v1
	v_add_u32_e32 v2, v4, v2
	v_cmp_ne_u32_e32 vcc, v3, v2
	s_and_saveexec_b64 s[8:9], vcc
	s_xor_b64 s[8:9], exec, s[8:9]
	s_cbranch_execz .LBB0_2301
	s_waitcnt lgkmcnt(0)
	v_add_u32_e32 v4, 1, v1
	v_mul_lo_u32 v4, v4, v0
	v_mov_b32_e32 v0, 0x3000
	global_load_dword v0, v0, s[4:5] offset:1024 sc1
	s_add_u32 s14, s4, 0x3400
	s_addc_u32 s15, s5, 0
	s_waitcnt vmcnt(0)
	v_cmp_lt_u32_e32 vcc, v0, v4
	s_and_saveexec_b64 s[12:13], vcc
	s_cbranch_execz .LBB0_2300
	s_mov_b32 s40, 1
	s_mov_b64 s[28:29], 0
	s_branch .LBB0_2291

; __device__ __forceinline__ unsigned xb_ld(unsigned* p)              { return __hip_atomic_load(p, __ATOMIC_RELAXED, __HIP_MEMORY_SCOPE_AGENT); }
; #define XB_SPIN(cond, bar) do { unsigned _sp = 0; while (cond) { __builtin_amdgcn_s_sleep(1); \
;     if ((++_sp & 255u) == 0u) { if (xb_ld(&(bar)[XB_TMO])) break; if (_sp > XB_SPIN_CAP) { atomicAdd(&(bar)[XB_TMO], 1u); break; } } } } while (0)
; __device__ __forceinline__ void xcd_barrier(const XcdBarrier& b) {
;     ...
;             XB_SPIN(xb_ld(&bar[XB_XGEN(b.x)]) == gen, bar);
.LBB0_2293:
	global_load_dword v0, v33, s[14:15] sc1
	s_add_i32 s40, s40, 1
	s_mov_b64 s[36:37], -1
	s_waitcnt vmcnt(0)
	v_cmp_ge_u32_e32 vcc, v0, v4
	s_orn2_b64 s[34:35], vcc, exec
	s_branch .LBB0_2290

; __device__ __forceinline__ unsigned xb_ld(unsigned* p)              { return __hip_atomic_load(p, __ATOMIC_RELAXED, __HIP_MEMORY_SCOPE_AGENT); }
; __device__ __forceinline__ unsigned xb_add(unsigned* p, unsigned v) { return __hip_atomic_fetch_add(p, v, __ATOMIC_RELAXED, __HIP_MEMORY_SCOPE_AGENT); }
; #define XB_SPIN(cond, bar) do { unsigned _sp = 0; while (cond) { __builtin_amdgcn_s_sleep(1); \
;     if ((++_sp & 255u) == 0u) { if (xb_ld(&(bar)[XB_TMO])) break; if (_sp > XB_SPIN_CAP) { atomicAdd(&(bar)[XB_TMO], 1u); break; } } } } while (0)
; __device__ __forceinline__ void xcd_barrier(const XcdBarrier& b) {
;     ...
;             const unsigned og = xb_add(&bar[XB_TOP], 1u);
;             const unsigned tg = og / nx;
;             if (og + 1u == (tg + 1u) * nx) xb_add(&bar[XB_TOPGEN], 1u);
;             else XB_SPIN(xb_ld(&bar[XB_TOPGEN]) == tg, bar);
.LBB0_2304:
	s_or_b64 exec, exec, s[12:13]
	s_waitcnt vmcnt(0)
	v_readfirstlane_b32 s8, v2
	v_cvt_f32_u32_e32 v2, v0
	v_sub_u32_e32 v3, 0, v0
	v_add_u32_e32 v1, s8, v1
	s_add_u32 s8, s4, 0x3400
	v_rcp_iflag_f32_e32 v2, v2
	s_addc_u32 s9, s5, 0
	s_mov_b64 s[14:15], 0
	v_mul_f32_e32 v2, 0x4f7ffffe, v2
	v_cvt_u32_f32_e32 v2, v2
	v_mul_lo_u32 v3, v3, v2
	v_mul_hi_u32 v3, v2, v3
	v_add_u32_e32 v2, v2, v3
	v_mul_hi_u32 v2, v1, v2
	v_mul_lo_u32 v3, v2, v0
	v_sub_u32_e32 v3, v1, v3
	v_cmp_ge_u32_e32 vcc, v3, v0
	v_add_u32_e32 v4, 1, v2
	v_add_u32_e32 v1, 1, v1
	v_cndmask_b32_e32 v2, v2, v4, vcc
	v_sub_u32_e32 v4, v3, v0
	v_cndmask_b32_e32 v3, v3, v4, vcc
	v_cmp_ge_u32_e32 vcc, v3, v0
	v_add_u32_e32 v3, 1, v2
	s_nop 0
	v_cndmask_b32_e32 v2, v2, v3, vcc
	v_mul_lo_u32 v3, v0, v2
	v_add_u32_e32 v0, v3, v0
	v_mov_b32_e32 v5, v0
	v_cmp_ne_u32_e32 vcc, v1, v0
	v_mov_b64_e32 v[0:1], s[8:9]
	s_and_saveexec_b64 s[12:13], vcc
	s_cbranch_execz .LBB0_2316
	global_load_dword v0, v33, s[8:9] sc1
	s_mov_b64 s[30:31], 0
	s_waitcnt vmcnt(0)
	v_cmp_lt_u32_e32 vcc, v0, v5
	s_and_saveexec_b64 s[28:29], vcc
	s_cbranch_execz .LBB0_2315
	s_add_u32 s14, s4, 0x200
	s_addc_u32 s15, s5, 0
	s_mov_b32 s40, 1
	s_mov_b64 s[4:5], 0
	s_branch .LBB0_2308

; __device__ __forceinline__ unsigned xb_ld(unsigned* p)              { return __hip_atomic_load(p, __ATOMIC_RELAXED, __HIP_MEMORY_SCOPE_AGENT); }
; #define XB_SPIN(cond, bar) do { unsigned _sp = 0; while (cond) { __builtin_amdgcn_s_sleep(1); \
;     if ((++_sp & 255u) == 0u) { if (xb_ld(&(bar)[XB_TMO])) break; if (_sp > XB_SPIN_CAP) { atomicAdd(&(bar)[XB_TMO], 1u); break; } } } } while (0)
; __device__ __forceinline__ void xcd_barrier(const XcdBarrier& b) {
;     ...
;             else XB_SPIN(xb_ld(&bar[XB_TOPGEN]) == tg, bar);
.LBB0_2310:
	global_load_dword v0, v33, s[8:9] sc1
	s_add_i32 s40, s40, 1
	s_mov_b64 s[36:37], -1
	s_waitcnt vmcnt(0)
	v_cmp_ge_u32_e32 vcc, v0, v5
	s_orn2_b64 s[34:35], vcc, exec
	s_branch .LBB0_2307

; __device__ __forceinline__ unsigned xb_add(unsigned* p, unsigned v) { return __hip_atomic_fetch_add(p, v, __ATOMIC_RELAXED, __HIP_MEMORY_SCOPE_AGENT); }
; __device__ __forceinline__ void xcd_barrier(const XcdBarrier& b) {
;     ...
;             __builtin_amdgcn_fence(__ATOMIC_ACQUIRE, "agent");
;             xb_add(&bar[XB_XGEN(b.x)], 1u);
;             asm volatile("s_waitcnt vmcnt(0)" ::: "memory");
.LBB0_2318:
	s_or_b64 exec, exec, s[4:5]
	s_mov_b64 s[4:5], exec
	v_mbcnt_lo_u32_b32 v0, s4, 0
	v_mbcnt_hi_u32_b32 v0, s5, v0
	v_cmp_eq_u32_e32 vcc, 0, v0
	s_waitcnt vmcnt(0)
	buffer_inv sc1
	s_and_saveexec_b64 s[8:9], vcc
	s_cbranch_execz .LBB0_2320
	s_bcnt1_i32_b64 s4, s[4:5]
	v_mov_b32_e32 v0, s4
	v_mov_b32_e32 v1, 0x2000
.LBB0_2320:
	s_or_b64 exec, exec, s[8:9]
	s_waitcnt vmcnt(0)

; __device__ __forceinline__ unsigned xb_ld(unsigned* p)              { return __hip_atomic_load(p, __ATOMIC_RELAXED, __HIP_MEMORY_SCOPE_AGENT); }
; __device__ __forceinline__ unsigned xb_add(unsigned* p, unsigned v) { return __hip_atomic_fetch_add(p, v, __ATOMIC_RELAXED, __HIP_MEMORY_SCOPE_AGENT); }
; #define XB_SPIN(cond, bar) do { unsigned _sp = 0; while (cond) { __builtin_amdgcn_s_sleep(1); \
;     if ((++_sp & 255u) == 0u) { if (xb_ld(&(bar)[XB_TMO])) break; if (_sp > XB_SPIN_CAP) { atomicAdd(&(bar)[XB_TMO], 1u); break; } } } } while (0)
; __device__ __forceinline__ void xcd_barrier(const XcdBarrier& b) {
;     ...
;         const unsigned old = xb_add(&bar[XB_XSUB(b.x)], 1u);
;         const unsigned gen = old / nloc;
;         if (old + 1u == (gen + 1u) * nloc) {
;             __builtin_amdgcn_fence(__ATOMIC_RELEASE, "agent");
;             asm volatile("s_waitcnt vmcnt(0)" ::: "memory");
;             const unsigned og = xb_add(&bar[XB_TOP], 1u);
;             const unsigned tg = og / nx;
;             if (og + 1u == (tg + 1u) * nx) xb_add(&bar[XB_TOPGEN], 1u);
;             else XB_SPIN(xb_ld(&bar[XB_TOPGEN]) == tg, bar);
;             __builtin_amdgcn_fence(__ATOMIC_ACQUIRE, "agent");
;             xb_add(&bar[XB_XGEN(b.x)], 1u);
;             asm volatile("s_waitcnt vmcnt(0)" ::: "memory");
;         } else {
;             XB_SPIN(xb_ld(&bar[XB_XGEN(b.x)]) == gen, bar);
.LBB0_2353:
	s_or_b64 exec, exec, s[12:13]
	v_cvt_f32_u32_e32 v4, v2
	s_waitcnt vmcnt(0)
	v_readfirstlane_b32 s8, v3
	v_sub_u32_e32 v3, 0, v2
	v_rcp_iflag_f32_e32 v4, v4
	v_add_u32_e32 v5, s8, v1
	v_mul_f32_e32 v4, 0x4f7ffffe, v4
	v_cvt_u32_f32_e32 v4, v4
	v_mul_lo_u32 v1, v3, v4
	v_mul_hi_u32 v1, v4, v1
	v_add_u32_e32 v1, v4, v1
	v_mul_hi_u32 v1, v5, v1
	v_mul_lo_u32 v3, v1, v2
	v_sub_u32_e32 v3, v5, v3
	v_add_u32_e32 v4, 1, v1
	v_cmp_ge_u32_e32 vcc, v3, v2
	s_nop 1
	v_cndmask_b32_e32 v1, v1, v4, vcc
	v_sub_u32_e32 v4, v3, v2
	v_cndmask_b32_e32 v3, v3, v4, vcc
	v_add_u32_e32 v4, 1, v1
	v_cmp_ge_u32_e32 vcc, v3, v2
	v_add_u32_e32 v3, 1, v5
	s_nop 0
	v_cndmask_b32_e32 v1, v1, v4, vcc
	v_mul_lo_u32 v4, v2, v1
	v_add_u32_e32 v2, v4, v2
	v_cmp_ne_u32_e32 vcc, v3, v2
	s_and_saveexec_b64 s[8:9], vcc
	s_xor_b64 s[8:9], exec, s[8:9]
	s_cbranch_execz .LBB0_2367
	s_waitcnt lgkmcnt(0)
	v_add_u32_e32 v4, 1, v1
	v_mul_lo_u32 v4, v4, v0
	v_mov_b32_e32 v0, 0x3000
	global_load_dword v0, v0, s[4:5] offset:1024 sc1
	s_add_u32 s14, s4, 0x3400
	s_addc_u32 s15, s5, 0
	s_waitcnt vmcnt(0)
	v_cmp_lt_u32_e32 vcc, v0, v4
	s_and_saveexec_b64 s[12:13], vcc
	s_cbranch_execz .LBB0_2366
	s_mov_b32 s38, 1
	s_mov_b64 s[24:25], 0
	s_branch .LBB0_2357

; __device__ __forceinline__ unsigned xb_ld(unsigned* p)              { return __hip_atomic_load(p, __ATOMIC_RELAXED, __HIP_MEMORY_SCOPE_AGENT); }
; #define XB_SPIN(cond, bar) do { unsigned _sp = 0; while (cond) { __builtin_amdgcn_s_sleep(1); \
;     if ((++_sp & 255u) == 0u) { if (xb_ld(&(bar)[XB_TMO])) break; if (_sp > XB_SPIN_CAP) { atomicAdd(&(bar)[XB_TMO], 1u); break; } } } } while (0)
; __device__ __forceinline__ void xcd_barrier(const XcdBarrier& b) {
;     ...
;             XB_SPIN(xb_ld(&bar[XB_XGEN(b.x)]) == gen, bar);
.LBB0_2359:
	global_load_dword v0, v33, s[14:15] sc1
	s_add_i32 s38, s38, 1
	s_mov_b64 s[34:35], -1
	s_waitcnt vmcnt(0)
	v_cmp_ge_u32_e32 vcc, v0, v4
	s_orn2_b64 s[30:31], vcc, exec
	s_branch .LBB0_2356

; __device__ __forceinline__ unsigned xb_ld(unsigned* p)              { return __hip_atomic_load(p, __ATOMIC_RELAXED, __HIP_MEMORY_SCOPE_AGENT); }
; __device__ __forceinline__ unsigned xb_add(unsigned* p, unsigned v) { return __hip_atomic_fetch_add(p, v, __ATOMIC_RELAXED, __HIP_MEMORY_SCOPE_AGENT); }
; #define XB_SPIN(cond, bar) do { unsigned _sp = 0; while (cond) { __builtin_amdgcn_s_sleep(1); \
;     if ((++_sp & 255u) == 0u) { if (xb_ld(&(bar)[XB_TMO])) break; if (_sp > XB_SPIN_CAP) { atomicAdd(&(bar)[XB_TMO], 1u); break; } } } } while (0)
; __device__ __forceinline__ void xcd_barrier(const XcdBarrier& b) {
;     ...
;             const unsigned og = xb_add(&bar[XB_TOP], 1u);
;             const unsigned tg = og / nx;
;             if (og + 1u == (tg + 1u) * nx) xb_add(&bar[XB_TOPGEN], 1u);
;             else XB_SPIN(xb_ld(&bar[XB_TOPGEN]) == tg, bar);
.LBB0_2370:
	s_or_b64 exec, exec, s[12:13]
	v_cvt_f32_u32_e32 v3, v0
	s_waitcnt vmcnt(0)
	v_readfirstlane_b32 s8, v2
	s_mov_b64 s[14:15], 0
	v_rcp_iflag_f32_e32 v3, v3
	v_add_u32_e32 v1, s8, v1
	v_add_u32_e32 v4, 1, v1
	s_add_u32 s8, s4, 0x3400
	v_mul_f32_e32 v2, 0x4f7ffffe, v3
	v_cvt_u32_f32_e32 v2, v2
	v_sub_u32_e32 v3, 0, v0
	s_addc_u32 s9, s5, 0
	v_mul_lo_u32 v3, v3, v2
	v_mul_hi_u32 v3, v2, v3
	v_add_u32_e32 v2, v2, v3
	v_mul_hi_u32 v2, v1, v2
	v_mul_lo_u32 v3, v2, v0
	v_sub_u32_e32 v1, v1, v3
	v_add_u32_e32 v5, 1, v2
	v_cmp_ge_u32_e32 vcc, v1, v0
	v_sub_u32_e32 v3, v1, v0
	s_nop 0
	v_cndmask_b32_e32 v2, v2, v5, vcc
	v_cndmask_b32_e32 v1, v1, v3, vcc
	v_add_u32_e32 v3, 1, v2
	v_cmp_ge_u32_e32 vcc, v1, v0
	s_nop 1
	v_cndmask_b32_e32 v2, v2, v3, vcc
	v_mul_lo_u32 v1, v0, v2
	v_add_u32_e32 v0, v1, v0
	v_mov_b32_e32 v5, v0
	v_cmp_ne_u32_e32 vcc, v4, v0
	v_mov_b64_e32 v[0:1], s[8:9]
	s_and_saveexec_b64 s[12:13], vcc
	s_cbranch_execz .LBB0_2382
	global_load_dword v0, v33, s[8:9] sc1
	s_mov_b64 s[28:29], 0
	s_waitcnt vmcnt(0)
	v_cmp_lt_u32_e32 vcc, v0, v5
	s_and_saveexec_b64 s[24:25], vcc
	s_cbranch_execz .LBB0_2381
	s_add_u32 s14, s4, 0x200
	s_addc_u32 s15, s5, 0
	s_mov_b32 s38, 1
	s_mov_b64 s[4:5], 0
	s_branch .LBB0_2374

; __device__ __forceinline__ unsigned xb_ld(unsigned* p)              { return __hip_atomic_load(p, __ATOMIC_RELAXED, __HIP_MEMORY_SCOPE_AGENT); }
; #define XB_SPIN(cond, bar) do { unsigned _sp = 0; while (cond) { __builtin_amdgcn_s_sleep(1); \
;     if ((++_sp & 255u) == 0u) { if (xb_ld(&(bar)[XB_TMO])) break; if (_sp > XB_SPIN_CAP) { atomicAdd(&(bar)[XB_TMO], 1u); break; } } } } while (0)
; __device__ __forceinline__ void xcd_barrier(const XcdBarrier& b) {
;     ...
;             else XB_SPIN(xb_ld(&bar[XB_TOPGEN]) == tg, bar);
.LBB0_2376:
	global_load_dword v0, v33, s[8:9] sc1
	s_add_i32 s38, s38, 1
	s_mov_b64 s[34:35], -1
	s_waitcnt vmcnt(0)
	v_cmp_ge_u32_e32 vcc, v0, v5
	s_orn2_b64 s[30:31], vcc, exec
	s_branch .LBB0_2373

; __device__ __forceinline__ unsigned xb_add(unsigned* p, unsigned v) { return __hip_atomic_fetch_add(p, v, __ATOMIC_RELAXED, __HIP_MEMORY_SCOPE_AGENT); }
; __device__ __forceinline__ void xcd_barrier(const XcdBarrier& b) {
;     ...
;             __builtin_amdgcn_fence(__ATOMIC_ACQUIRE, "agent");
;             xb_add(&bar[XB_XGEN(b.x)], 1u);
;             asm volatile("s_waitcnt vmcnt(0)" ::: "memory");
.LBB0_2384:
	s_or_b64 exec, exec, s[4:5]
	s_mov_b64 s[4:5], exec
	v_mbcnt_lo_u32_b32 v0, s4, 0
	v_mbcnt_hi_u32_b32 v0, s5, v0
	v_cmp_eq_u32_e32 vcc, 0, v0
	s_waitcnt vmcnt(0)
	buffer_inv sc1
	s_and_saveexec_b64 s[8:9], vcc
	s_cbranch_execz .LBB0_2018
	s_bcnt1_i32_b64 s4, s[4:5]
	v_mov_b32_e32 v0, s4
	v_mov_b32_e32 v1, 0x2000
	s_branch .LBB0_2018
